# gates epilogue: first 5 second-half slot loads issued with the first half's loads (dead operand regs), copied into place later
# baseline (speedup 1.0000x reference)
;     __device__ __forceinline__ void operator()(const pg8::f32x4 (&acc)[2][2][4][2], const pg8::Unit& u, int wr, int wc, int fr, int fq) const {
;     ...
;             for (int m = 0; m < 4; ++m)
; #pragma unroll
;                 for (int bj = 0; bj < 2; ++bj) f.pre(row0 + ai * 128 + m * 16, col0 + bj * 128, ld[m][bj]);
;     __device__ __forceinline__ void pre(int row, int col, u32x4 (&ld)[2]) const {
;         const int reg = col >> 10, c = col & 1023;
;         ld[0] = *(const u32x4*)(buf(reg) + (size_t)row * DM + c); }
.Lgates_skipld_1:
	v_or_b32_e32 v102, 32, v100
	v_or_b32_e32 v100, 48, v100
	v_ashrrev_i32_e32 v103, 31, v102
	v_ashrrev_i32_e32 v101, 31, v100
	v_lshlrev_b64 v[192:193], 11, v[102:103]
	v_lshlrev_b64 v[190:191], 11, v[100:101]
	v_lshl_add_u64 v[102:103], s[52:53], 0, v[192:193]
	v_lshl_add_u64 v[100:101], s[52:53], 0, v[190:191]
	v_lshl_add_u64 v[102:103], v[102:103], 0, s[96:97]
	v_lshl_add_u64 v[100:101], v[100:101], 0, s[96:97]
	v_lshl_add_u64 v[102:103], v[102:103], 0, v[2:3]
	v_lshl_add_u64 v[100:101], v[100:101], 0, v[2:3]
	s_cbranch_vccz .Lgates_skipld_2
	global_load_dwordx4 v[136:139], v[102:103], off
	global_load_dwordx4 v[124:127], v[102:103], off offset:256
	global_load_dwordx4 v[112:115], v[100:101], off
	s_nop 0
	global_load_dwordx4 v[100:103], v[100:101], off offset:256
	v_lshl_add_u64 v[214:215], v[188:189], 0, s[10:11]
	v_lshl_add_u64 v[214:215], s[52:53], 0, v[214:215]
	v_lshl_add_u64 v[214:215], v[214:215], 0, s[96:97]
	v_lshl_add_u64 v[214:215], v[214:215], 0, v[2:3]
	global_load_dwordx4 v[216:219], v[214:215], off
	global_load_dwordx4 v[224:227], v[214:215], off offset:256
	s_mov_b64 s[98:99], 0x48000
	v_lshl_add_u64 v[214:215], v[188:189], 0, s[98:99]
	v_lshl_add_u64 v[214:215], s[52:53], 0, v[214:215]
	v_lshl_add_u64 v[214:215], v[214:215], 0, s[96:97]
	v_lshl_add_u64 v[214:215], v[214:215], 0, v[2:3]
	global_load_dwordx4 v[228:231], v[214:215], off
	global_load_dwordx4 v[232:235], v[214:215], off offset:256
	s_mov_b64 s[98:99], 0x50000
	v_lshl_add_u64 v[214:215], v[188:189], 0, s[98:99]
	v_lshl_add_u64 v[214:215], s[52:53], 0, v[214:215]
	v_lshl_add_u64 v[214:215], v[214:215], 0, s[96:97]
	v_lshl_add_u64 v[214:215], v[214:215], 0, v[2:3]
	global_load_dwordx4 v[236:239], v[214:215], off
.Lgates_skipld_2:
	s_waitcnt vmcnt(0)
	v_lshlrev_b32_e32 v170, 16, v208
	v_mul_f32_e32 v214, 0xbfb8aa3b, v144
	v_mul_f32_e32 v144, v144, v170
	v_mul_f32_e32 v170, 0xbfb8aa3b, v145
	v_exp_f32_e32 v170, v170
	v_and_b32_e32 v171, 0xffff0000, v208
	v_mul_f32_e32 v145, v145, v171
	v_lshlrev_b32_e32 v208, 16, v209
	v_add_f32_e32 v170, 1.0, v170
	v_rcp_f32_e32 v170, v170
	v_and_b32_e32 v209, 0xffff0000, v209
	v_lshlrev_b32_e32 v212, 16, v210
	v_and_b32_e32 v210, 0xffff0000, v210
	v_mul_f32_e32 v145, v170, v145
	v_cndmask_b32_e32 v145, v170, v145, vcc
	v_mul_f32_e32 v170, 0xbfb8aa3b, v146
	v_exp_f32_e32 v170, v170
	v_mul_f32_e32 v146, v146, v208
	v_lshlrev_b32_e32 v213, 16, v211
	v_exp_f32_e32 v214, v214
	v_add_f32_e32 v170, 1.0, v170
	v_rcp_f32_e32 v170, v170
	s_add_u32 s45, s30, s96
	s_addc_u32 s50, s31, 0
	v_add_f32_e32 v214, 1.0, v214
	v_mul_f32_e32 v146, v170, v146
	v_cndmask_b32_e32 v146, v170, v146, vcc
	v_mul_f32_e32 v170, 0xbfb8aa3b, v147
	v_exp_f32_e32 v170, v170
	v_mul_f32_e32 v147, v147, v209
	s_add_u32 s6, s45, s6
	v_rcp_f32_e32 v214, v214
	v_add_f32_e32 v170, 1.0, v170
	v_rcp_f32_e32 v170, v170
	s_addc_u32 s45, s50, 0
	s_add_u32 s6, s6, s7
	v_and_b32_e32 v211, 0xffff0000, v211
	v_mul_f32_e32 v147, v170, v147
	v_cndmask_b32_e32 v147, v170, v147, vcc
	v_mul_f32_e32 v170, 0xbfb8aa3b, v140
	v_exp_f32_e32 v170, v170
	v_mul_f32_e32 v140, v140, v212
	s_addc_u32 s7, s45, 0
	s_add_u32 s50, s6, s43
	v_add_f32_e32 v170, 1.0, v170
	v_rcp_f32_e32 v170, v170
	v_mul_f32_e32 v144, v214, v144
	s_addc_u32 s51, s7, 0
	v_cndmask_b32_e32 v144, v214, v144, vcc
	v_mul_f32_e32 v140, v170, v140
	v_cndmask_b32_e32 v170, v170, v140, vcc
	v_mul_f32_e32 v140, 0xbfb8aa3b, v141
	v_exp_f32_e32 v140, v140
	v_mul_f32_e32 v141, v141, v210
	v_add_f32_e32 v140, 1.0, v140
	v_rcp_f32_e32 v140, v140
	s_nop 0
	v_mul_f32_e32 v141, v140, v141
	v_cndmask_b32_e32 v171, v140, v141, vcc
	v_mul_f32_e32 v140, 0xbfb8aa3b, v142
	v_exp_f32_e32 v140, v140
	v_mul_f32_e32 v141, v142, v213
	v_cvt_pk_bf16_f32 v142, v144, v145
	v_cvt_pk_bf16_f32 v144, v170, v171
	v_add_f32_e32 v140, 1.0, v140
	v_rcp_f32_e32 v140, v140
	s_nop 0
	v_mul_f32_e32 v141, v140, v141
	v_cndmask_b32_e32 v208, v140, v141, vcc
	v_mul_f32_e32 v140, 0xbfb8aa3b, v143
	v_exp_f32_e32 v140, v140
	v_mul_f32_e32 v141, v143, v211
	v_cvt_pk_bf16_f32 v143, v146, v147
	v_lshlrev_b32_e32 v146, 16, v158
	v_add_f32_e32 v140, 1.0, v140
	v_rcp_f32_e32 v140, v140
	v_and_b32_e32 v147, 0xffff0000, v158
	v_mul_f32_e32 v158, 0xbfb8aa3b, v132
	v_exp_f32_e32 v158, v158
	v_mul_f32_e32 v141, v140, v141
	v_cndmask_b32_e32 v209, v140, v141, vcc
	v_lshl_add_u64 v[140:141], s[50:51], 0, v[188:189]
	v_lshl_add_u64 v[140:141], v[140:141], 0, v[2:3]
	v_cvt_pk_bf16_f32 v145, v208, v209
	global_store_dwordx4 v[140:141], v[142:145], off
	v_add_f32_e32 v158, 1.0, v158
	v_rcp_f32_e32 v158, v158
	v_lshlrev_b32_e32 v142, 16, v156
	v_mul_f32_e32 v132, v132, v142
	v_mul_f32_e32 v142, 0xbfb8aa3b, v133
	v_exp_f32_e32 v142, v142
	v_and_b32_e32 v143, 0xffff0000, v156
	v_mul_f32_e32 v133, v133, v143
	v_lshlrev_b32_e32 v144, 16, v157
	v_add_f32_e32 v142, 1.0, v142
	v_rcp_f32_e32 v142, v142
	v_and_b32_e32 v145, 0xffff0000, v157
	v_lshlrev_b32_e32 v156, 16, v159
	v_and_b32_e32 v157, 0xffff0000, v159
	v_mul_f32_e32 v133, v142, v133
	v_cndmask_b32_e32 v133, v142, v133, vcc
	v_mul_f32_e32 v142, 0xbfb8aa3b, v134
	v_exp_f32_e32 v142, v142
	v_mul_f32_e32 v134, v134, v144
	v_mul_f32_e32 v132, v158, v132
	v_cndmask_b32_e32 v132, v158, v132, vcc
	v_add_f32_e32 v142, 1.0, v142
	v_rcp_f32_e32 v142, v142
	s_nop 0
	v_mul_f32_e32 v134, v142, v134
	v_cndmask_b32_e32 v134, v142, v134, vcc
	v_mul_f32_e32 v142, 0xbfb8aa3b, v135
	v_exp_f32_e32 v142, v142
	v_mul_f32_e32 v135, v135, v145
	v_add_f32_e32 v142, 1.0, v142
	v_rcp_f32_e32 v142, v142
	s_nop 0
	v_mul_f32_e32 v135, v142, v135
	v_cndmask_b32_e32 v135, v142, v135, vcc
	v_mul_f32_e32 v142, 0xbfb8aa3b, v128
	v_exp_f32_e32 v142, v142
	v_mul_f32_e32 v128, v128, v146
	v_add_f32_e32 v142, 1.0, v142
	v_rcp_f32_e32 v142, v142
	s_nop 0
	v_mul_f32_e32 v128, v142, v128
	v_cndmask_b32_e32 v142, v142, v128, vcc
	v_mul_f32_e32 v128, 0xbfb8aa3b, v129
	v_exp_f32_e32 v128, v128
	v_mul_f32_e32 v129, v129, v147
	v_add_f32_e32 v128, 1.0, v128
	v_rcp_f32_e32 v128, v128
	s_nop 0
	v_mul_f32_e32 v129, v128, v129
	v_cndmask_b32_e32 v143, v128, v129, vcc
	v_mul_f32_e32 v128, 0xbfb8aa3b, v130
	v_exp_f32_e32 v128, v128
	v_mul_f32_e32 v129, v130, v156
	v_cvt_pk_bf16_f32 v130, v142, v143
	v_add_f32_e32 v128, 1.0, v128
	v_rcp_f32_e32 v128, v128
	s_nop 0
	v_mul_f32_e32 v129, v128, v129
	v_cndmask_b32_e32 v144, v128, v129, vcc
	v_mul_f32_e32 v128, 0xbfb8aa3b, v131
	v_exp_f32_e32 v128, v128
	v_mul_f32_e32 v129, v131, v157
	v_add_f32_e32 v128, 1.0, v128
	v_rcp_f32_e32 v128, v128
	s_nop 0
	v_mul_f32_e32 v129, v128, v129
	v_cndmask_b32_e32 v131, v128, v129, vcc
	v_cvt_pk_bf16_f32 v128, v132, v133
	v_cvt_pk_bf16_f32 v129, v134, v135
	v_cvt_pk_bf16_f32 v131, v144, v131
	global_store_dwordx4 v[140:141], v[128:131], off offset:256
	v_mul_f32_e32 v140, 0xbfb8aa3b, v120
	v_lshlrev_b32_e32 v132, 16, v154
	v_lshlrev_b32_e32 v128, 16, v152
	v_mul_f32_e32 v120, v120, v128
	v_mul_f32_e32 v128, 0xbfb8aa3b, v121
	v_exp_f32_e32 v128, v128
	v_and_b32_e32 v129, 0xffff0000, v152
	v_mul_f32_e32 v121, v121, v129
	v_lshlrev_b32_e32 v130, 16, v153
	v_add_f32_e32 v128, 1.0, v128
	v_rcp_f32_e32 v128, v128
	v_and_b32_e32 v131, 0xffff0000, v153
	v_and_b32_e32 v133, 0xffff0000, v154
	v_lshlrev_b32_e32 v134, 16, v155
	v_mul_f32_e32 v121, v128, v121
	v_cndmask_b32_e32 v121, v128, v121, vcc
	v_mul_f32_e32 v128, 0xbfb8aa3b, v122
	v_exp_f32_e32 v128, v128
	v_mul_f32_e32 v122, v122, v130
	v_exp_f32_e32 v140, v140
	v_and_b32_e32 v135, 0xffff0000, v155
	v_add_f32_e32 v128, 1.0, v128
	v_rcp_f32_e32 v128, v128
	v_add_f32_e32 v140, 1.0, v140
	v_rcp_f32_e32 v140, v140
	v_mul_f32_e32 v122, v128, v122
	v_cndmask_b32_e32 v122, v128, v122, vcc
	v_mul_f32_e32 v128, 0xbfb8aa3b, v123
	v_exp_f32_e32 v128, v128
	v_mul_f32_e32 v123, v123, v131
	v_mul_f32_e32 v120, v140, v120
	v_cndmask_b32_e32 v120, v140, v120, vcc
	v_add_f32_e32 v128, 1.0, v128
	v_rcp_f32_e32 v128, v128
	s_nop 0
	v_mul_f32_e32 v123, v128, v123
	v_cndmask_b32_e32 v123, v128, v123, vcc
	v_mul_f32_e32 v128, 0xbfb8aa3b, v116
	v_exp_f32_e32 v128, v128
	v_mul_f32_e32 v116, v116, v132
	v_add_f32_e32 v128, 1.0, v128
	v_rcp_f32_e32 v128, v128
	s_nop 0
	v_mul_f32_e32 v116, v128, v116
	v_cndmask_b32_e32 v128, v128, v116, vcc
	v_mul_f32_e32 v116, 0xbfb8aa3b, v117
	v_exp_f32_e32 v116, v116
	v_mul_f32_e32 v117, v117, v133
	v_add_f32_e32 v116, 1.0, v116
	v_rcp_f32_e32 v116, v116
	s_nop 0
	v_mul_f32_e32 v117, v116, v117
	v_cndmask_b32_e32 v129, v116, v117, vcc
	v_mul_f32_e32 v116, 0xbfb8aa3b, v118
	v_exp_f32_e32 v116, v116
	v_mul_f32_e32 v117, v118, v134
	v_cvt_pk_bf16_f32 v118, v120, v121
	v_cvt_pk_bf16_f32 v120, v128, v129
	v_add_f32_e32 v116, 1.0, v116
	v_rcp_f32_e32 v116, v116
	v_lshlrev_b32_e32 v128, 16, v151
	v_and_b32_e32 v129, 0xffff0000, v151
	v_mul_f32_e32 v117, v116, v117
	v_cndmask_b32_e32 v130, v116, v117, vcc
	v_mul_f32_e32 v116, 0xbfb8aa3b, v119
	v_exp_f32_e32 v116, v116
	v_mul_f32_e32 v117, v119, v135
	v_cvt_pk_bf16_f32 v119, v122, v123
	v_lshlrev_b32_e32 v122, 16, v150
	v_add_f32_e32 v116, 1.0, v116
	v_rcp_f32_e32 v116, v116
	v_and_b32_e32 v123, 0xffff0000, v150
	v_mul_f32_e32 v117, v116, v117
	v_cndmask_b32_e32 v131, v116, v117, vcc
	v_lshl_add_u64 v[116:117], s[50:51], 0, v[194:195]
	v_lshl_add_u64 v[116:117], v[116:117], 0, v[2:3]
	v_cvt_pk_bf16_f32 v121, v130, v131
	global_store_dwordx4 v[116:117], v[118:121], off
	v_mul_f32_e32 v130, 0xbfb8aa3b, v108
	v_exp_f32_e32 v130, v130
	v_lshlrev_b32_e32 v118, 16, v148
	v_mul_f32_e32 v108, v108, v118
	v_mul_f32_e32 v118, 0xbfb8aa3b, v109
	v_exp_f32_e32 v118, v118
	v_and_b32_e32 v119, 0xffff0000, v148
	v_mul_f32_e32 v109, v109, v119
	v_lshlrev_b32_e32 v120, 16, v149
	v_add_f32_e32 v118, 1.0, v118
	v_rcp_f32_e32 v118, v118
	v_and_b32_e32 v121, 0xffff0000, v149
	v_add_f32_e32 v130, 1.0, v130
	v_rcp_f32_e32 v130, v130
	v_mul_f32_e32 v109, v118, v109
	v_cndmask_b32_e32 v109, v118, v109, vcc
	v_mul_f32_e32 v118, 0xbfb8aa3b, v110
	v_exp_f32_e32 v118, v118
	v_mul_f32_e32 v110, v110, v120
	v_mul_f32_e32 v108, v130, v108
	v_cndmask_b32_e32 v108, v130, v108, vcc
	v_add_f32_e32 v118, 1.0, v118
	v_rcp_f32_e32 v118, v118
	s_nop 0
	v_mul_f32_e32 v110, v118, v110
	v_cndmask_b32_e32 v110, v118, v110, vcc
	v_mul_f32_e32 v118, 0xbfb8aa3b, v111
	v_exp_f32_e32 v118, v118
	v_mul_f32_e32 v111, v111, v121
	v_add_f32_e32 v118, 1.0, v118
	v_rcp_f32_e32 v118, v118
	s_nop 0
	v_mul_f32_e32 v111, v118, v111
	v_cndmask_b32_e32 v111, v118, v111, vcc
	v_mul_f32_e32 v118, 0xbfb8aa3b, v104
	v_exp_f32_e32 v118, v118
	v_mul_f32_e32 v104, v104, v122
	v_add_f32_e32 v118, 1.0, v118
	v_rcp_f32_e32 v118, v118
	s_nop 0
	v_mul_f32_e32 v104, v118, v104
	v_cndmask_b32_e32 v118, v118, v104, vcc
	v_mul_f32_e32 v104, 0xbfb8aa3b, v105
	v_exp_f32_e32 v104, v104
	v_mul_f32_e32 v105, v105, v123
	v_add_f32_e32 v104, 1.0, v104
	v_rcp_f32_e32 v104, v104
	s_nop 0
	v_mul_f32_e32 v105, v104, v105
	v_cndmask_b32_e32 v119, v104, v105, vcc
	v_mul_f32_e32 v104, 0xbfb8aa3b, v106
	v_exp_f32_e32 v104, v104
	v_mul_f32_e32 v105, v106, v128
	v_cvt_pk_bf16_f32 v106, v118, v119
	v_add_f32_e32 v104, 1.0, v104
	v_rcp_f32_e32 v104, v104
	s_nop 0
	v_mul_f32_e32 v105, v104, v105
	v_cndmask_b32_e32 v120, v104, v105, vcc
	v_mul_f32_e32 v104, 0xbfb8aa3b, v107
	v_exp_f32_e32 v104, v104
	v_mul_f32_e32 v105, v107, v129
	v_add_f32_e32 v104, 1.0, v104
	v_rcp_f32_e32 v104, v104
	s_nop 0
	v_mul_f32_e32 v105, v104, v105
	v_cndmask_b32_e32 v107, v104, v105, vcc
	v_cvt_pk_bf16_f32 v104, v108, v109
	v_cvt_pk_bf16_f32 v105, v110, v111
	v_cvt_pk_bf16_f32 v107, v120, v107
	global_store_dwordx4 v[116:117], v[104:107], off offset:256
	v_mul_f32_e32 v116, 0xbfb8aa3b, v96
	v_lshlrev_b32_e32 v108, 16, v138
	v_lshlrev_b32_e32 v104, 16, v136
	v_mul_f32_e32 v96, v96, v104
	v_mul_f32_e32 v104, 0xbfb8aa3b, v97
	v_exp_f32_e32 v104, v104
	v_and_b32_e32 v105, 0xffff0000, v136
	v_mul_f32_e32 v97, v97, v105
	v_lshlrev_b32_e32 v106, 16, v137
	v_add_f32_e32 v104, 1.0, v104
	v_rcp_f32_e32 v104, v104
	v_and_b32_e32 v107, 0xffff0000, v137
	v_and_b32_e32 v109, 0xffff0000, v138
	v_lshlrev_b32_e32 v110, 16, v139
	v_mul_f32_e32 v97, v104, v97
	v_cndmask_b32_e32 v97, v104, v97, vcc
	v_mul_f32_e32 v104, 0xbfb8aa3b, v98
	v_exp_f32_e32 v104, v104
	v_mul_f32_e32 v98, v98, v106
	v_exp_f32_e32 v116, v116
	v_and_b32_e32 v111, 0xffff0000, v139
	v_add_f32_e32 v104, 1.0, v104
	v_rcp_f32_e32 v104, v104
	v_add_f32_e32 v116, 1.0, v116
	v_rcp_f32_e32 v116, v116
	v_mul_f32_e32 v98, v104, v98
	v_cndmask_b32_e32 v98, v104, v98, vcc
	v_mul_f32_e32 v104, 0xbfb8aa3b, v99
	v_exp_f32_e32 v104, v104
	v_mul_f32_e32 v99, v99, v107
	v_mul_f32_e32 v96, v116, v96
	v_cndmask_b32_e32 v96, v116, v96, vcc
	v_add_f32_e32 v104, 1.0, v104
	v_rcp_f32_e32 v104, v104
	s_nop 0
	v_mul_f32_e32 v99, v104, v99
	v_cndmask_b32_e32 v99, v104, v99, vcc
	v_mul_f32_e32 v104, 0xbfb8aa3b, v92
	v_exp_f32_e32 v104, v104
	v_mul_f32_e32 v92, v92, v108
	v_add_f32_e32 v104, 1.0, v104
	v_rcp_f32_e32 v104, v104
	s_nop 0
	v_mul_f32_e32 v92, v104, v92
	v_cndmask_b32_e32 v104, v104, v92, vcc
	v_mul_f32_e32 v92, 0xbfb8aa3b, v93
	v_exp_f32_e32 v92, v92
	v_mul_f32_e32 v93, v93, v109
	v_add_f32_e32 v92, 1.0, v92
	v_rcp_f32_e32 v92, v92
	s_nop 0
	v_mul_f32_e32 v93, v92, v93
	v_cndmask_b32_e32 v105, v92, v93, vcc
	v_mul_f32_e32 v92, 0xbfb8aa3b, v94
	v_exp_f32_e32 v92, v92
	v_mul_f32_e32 v93, v94, v110
	v_cvt_pk_bf16_f32 v94, v96, v97
	v_cvt_pk_bf16_f32 v96, v104, v105
	v_add_f32_e32 v92, 1.0, v92
	v_rcp_f32_e32 v92, v92
	v_lshlrev_b32_e32 v104, 16, v127
	v_and_b32_e32 v105, 0xffff0000, v127
	v_mul_f32_e32 v93, v92, v93
	v_cndmask_b32_e32 v106, v92, v93, vcc
	v_mul_f32_e32 v92, 0xbfb8aa3b, v95
	v_exp_f32_e32 v92, v92
	v_mul_f32_e32 v93, v95, v111
	v_cvt_pk_bf16_f32 v95, v98, v99
	v_lshlrev_b32_e32 v98, 16, v126
	v_add_f32_e32 v92, 1.0, v92
	v_rcp_f32_e32 v92, v92
	v_and_b32_e32 v99, 0xffff0000, v126
	v_mul_f32_e32 v93, v92, v93
	v_cndmask_b32_e32 v107, v92, v93, vcc
	v_lshl_add_u64 v[92:93], s[50:51], 0, v[192:193]
	v_lshl_add_u64 v[92:93], v[92:93], 0, v[2:3]
	v_cvt_pk_bf16_f32 v97, v106, v107
	global_store_dwordx4 v[92:93], v[94:97], off
	v_mul_f32_e32 v106, 0xbfb8aa3b, v88
	v_exp_f32_e32 v106, v106
	v_lshlrev_b32_e32 v94, 16, v124
	v_mul_f32_e32 v88, v88, v94
	v_mul_f32_e32 v94, 0xbfb8aa3b, v89
	v_exp_f32_e32 v94, v94
	v_and_b32_e32 v95, 0xffff0000, v124
	v_mul_f32_e32 v89, v89, v95
	v_lshlrev_b32_e32 v96, 16, v125
	v_add_f32_e32 v94, 1.0, v94
	v_rcp_f32_e32 v94, v94
	v_and_b32_e32 v97, 0xffff0000, v125
	v_add_f32_e32 v106, 1.0, v106
	v_rcp_f32_e32 v106, v106
	v_mul_f32_e32 v89, v94, v89
	v_cndmask_b32_e32 v89, v94, v89, vcc
	v_mul_f32_e32 v94, 0xbfb8aa3b, v90
	v_exp_f32_e32 v94, v94
	v_mul_f32_e32 v90, v90, v96
	v_mul_f32_e32 v88, v106, v88
	v_cndmask_b32_e32 v88, v106, v88, vcc
	v_add_f32_e32 v94, 1.0, v94
	v_rcp_f32_e32 v94, v94
	s_nop 0
	v_mul_f32_e32 v90, v94, v90
	v_cndmask_b32_e32 v90, v94, v90, vcc
	v_mul_f32_e32 v94, 0xbfb8aa3b, v91
	v_exp_f32_e32 v94, v94
	v_mul_f32_e32 v91, v91, v97
	v_add_f32_e32 v94, 1.0, v94
	v_rcp_f32_e32 v94, v94
	s_nop 0
	v_mul_f32_e32 v91, v94, v91
	v_cndmask_b32_e32 v91, v94, v91, vcc
	v_mul_f32_e32 v94, 0xbfb8aa3b, v84
	v_exp_f32_e32 v94, v94
	v_mul_f32_e32 v84, v84, v98
	v_add_f32_e32 v94, 1.0, v94
	v_rcp_f32_e32 v94, v94
	s_nop 0
	v_mul_f32_e32 v84, v94, v84
	v_cndmask_b32_e32 v94, v94, v84, vcc
	v_mul_f32_e32 v84, 0xbfb8aa3b, v85
	v_exp_f32_e32 v84, v84
	v_mul_f32_e32 v85, v85, v99
	v_add_f32_e32 v84, 1.0, v84
	v_rcp_f32_e32 v84, v84
	s_nop 0
	v_mul_f32_e32 v85, v84, v85
	v_cndmask_b32_e32 v95, v84, v85, vcc
	v_mul_f32_e32 v84, 0xbfb8aa3b, v86
	v_exp_f32_e32 v84, v84
	v_mul_f32_e32 v85, v86, v104
	v_cvt_pk_bf16_f32 v86, v94, v95
	v_add_f32_e32 v84, 1.0, v84
	v_rcp_f32_e32 v84, v84
	s_nop 0
	v_mul_f32_e32 v85, v84, v85
	v_cndmask_b32_e32 v96, v84, v85, vcc
	v_mul_f32_e32 v84, 0xbfb8aa3b, v87
	v_exp_f32_e32 v84, v84
	v_mul_f32_e32 v85, v87, v105
	v_add_f32_e32 v84, 1.0, v84
	v_rcp_f32_e32 v84, v84
	s_nop 0
	v_mul_f32_e32 v85, v84, v85
	v_cndmask_b32_e32 v87, v84, v85, vcc
	v_cvt_pk_bf16_f32 v84, v88, v89
	v_cvt_pk_bf16_f32 v85, v90, v91
	v_cvt_pk_bf16_f32 v87, v96, v87
	global_store_dwordx4 v[92:93], v[84:87], off offset:256
	v_mul_f32_e32 v92, 0xbfb8aa3b, v80
	v_lshlrev_b32_e32 v88, 16, v114
	v_lshlrev_b32_e32 v84, 16, v112
	v_mul_f32_e32 v80, v80, v84
	v_mul_f32_e32 v84, 0xbfb8aa3b, v81
	v_exp_f32_e32 v84, v84
	v_and_b32_e32 v85, 0xffff0000, v112
	v_mul_f32_e32 v81, v81, v85
	v_lshlrev_b32_e32 v86, 16, v113
	v_add_f32_e32 v84, 1.0, v84
	v_rcp_f32_e32 v84, v84
	v_and_b32_e32 v87, 0xffff0000, v113
	v_and_b32_e32 v89, 0xffff0000, v114
	v_lshlrev_b32_e32 v90, 16, v115
	v_mul_f32_e32 v81, v84, v81
	v_cndmask_b32_e32 v81, v84, v81, vcc
	v_mul_f32_e32 v84, 0xbfb8aa3b, v82
;     __device__ __forceinline__ void operator()(const pg8::f32x4 (&acc)[2][2][4][2], const pg8::Unit& u, int wr, int wc, int fr, int fq) const {
;     ...
;             for (int m = 0; m < 4; ++m)
; #pragma unroll
;                 for (int bj = 0; bj < 2; ++bj) f.pre(row0 + ai * 128 + m * 16, col0 + bj * 128, ld[m][bj]);
	v_exp_f32_e32 v84, v84
	v_mul_f32_e32 v82, v82, v86
	v_exp_f32_e32 v92, v92
	v_and_b32_e32 v91, 0xffff0000, v115
	v_add_f32_e32 v84, 1.0, v84
	v_rcp_f32_e32 v84, v84
	v_add_f32_e32 v92, 1.0, v92
	v_rcp_f32_e32 v92, v92
	v_mul_f32_e32 v82, v84, v82
	v_cndmask_b32_e32 v82, v84, v82, vcc
	v_mul_f32_e32 v84, 0xbfb8aa3b, v83
	v_exp_f32_e32 v84, v84
	v_mul_f32_e32 v83, v83, v87
	v_mul_f32_e32 v80, v92, v80
	v_cndmask_b32_e32 v80, v92, v80, vcc
	v_add_f32_e32 v84, 1.0, v84
	v_rcp_f32_e32 v84, v84
	s_nop 0
	v_mul_f32_e32 v83, v84, v83
	v_cndmask_b32_e32 v83, v84, v83, vcc
	v_mul_f32_e32 v84, 0xbfb8aa3b, v76
	v_exp_f32_e32 v84, v84
	v_mul_f32_e32 v76, v76, v88
	v_add_f32_e32 v84, 1.0, v84
	v_rcp_f32_e32 v84, v84
	s_nop 0
	v_mul_f32_e32 v76, v84, v76
	v_cndmask_b32_e32 v84, v84, v76, vcc
	v_mul_f32_e32 v76, 0xbfb8aa3b, v77
	v_exp_f32_e32 v76, v76
	v_mul_f32_e32 v77, v77, v89
	v_add_f32_e32 v76, 1.0, v76
	v_rcp_f32_e32 v76, v76
	s_nop 0
	v_mul_f32_e32 v77, v76, v77
	v_cndmask_b32_e32 v85, v76, v77, vcc
	v_mul_f32_e32 v76, 0xbfb8aa3b, v78
	v_exp_f32_e32 v76, v76
	v_mul_f32_e32 v77, v78, v90
	v_cvt_pk_bf16_f32 v78, v80, v81
	v_cvt_pk_bf16_f32 v80, v84, v85
	v_add_f32_e32 v76, 1.0, v76
	v_rcp_f32_e32 v76, v76
	v_lshlrev_b32_e32 v84, 16, v103
	v_and_b32_e32 v85, 0xffff0000, v103
	v_mul_f32_e32 v77, v76, v77
	v_cndmask_b32_e32 v86, v76, v77, vcc
	v_mul_f32_e32 v76, 0xbfb8aa3b, v79
	v_exp_f32_e32 v76, v76
	v_mul_f32_e32 v77, v79, v91
	v_cvt_pk_bf16_f32 v79, v82, v83
	v_lshlrev_b32_e32 v82, 16, v102
	v_add_f32_e32 v76, 1.0, v76
	v_rcp_f32_e32 v76, v76
	v_and_b32_e32 v83, 0xffff0000, v102
	v_mul_f32_e32 v77, v76, v77
	v_cndmask_b32_e32 v87, v76, v77, vcc
	v_lshl_add_u64 v[76:77], s[50:51], 0, v[190:191]
	v_lshl_add_u64 v[76:77], v[76:77], 0, v[2:3]
	v_cvt_pk_bf16_f32 v81, v86, v87
	global_store_dwordx4 v[76:77], v[78:81], off
	v_mul_f32_e32 v86, 0xbfb8aa3b, v72
	v_exp_f32_e32 v86, v86
	v_lshlrev_b32_e32 v78, 16, v100
	v_mul_f32_e32 v72, v72, v78
	v_mul_f32_e32 v78, 0xbfb8aa3b, v73
	v_exp_f32_e32 v78, v78
	v_and_b32_e32 v79, 0xffff0000, v100
	v_mul_f32_e32 v73, v73, v79
	v_lshlrev_b32_e32 v80, 16, v101
	v_add_f32_e32 v78, 1.0, v78
	v_rcp_f32_e32 v78, v78
	v_and_b32_e32 v81, 0xffff0000, v101
	v_add_f32_e32 v86, 1.0, v86
	v_rcp_f32_e32 v86, v86
	v_mul_f32_e32 v73, v78, v73
	v_cndmask_b32_e32 v73, v78, v73, vcc
	v_mul_f32_e32 v78, 0xbfb8aa3b, v74
	v_exp_f32_e32 v78, v78
	v_mul_f32_e32 v74, v74, v80
	v_mul_f32_e32 v72, v86, v72
	v_cndmask_b32_e32 v72, v86, v72, vcc
	v_add_f32_e32 v78, 1.0, v78
	v_rcp_f32_e32 v78, v78
	s_nop 0
	v_mul_f32_e32 v74, v78, v74
	v_cndmask_b32_e32 v74, v78, v74, vcc
	v_mul_f32_e32 v78, 0xbfb8aa3b, v75
	v_exp_f32_e32 v78, v78
	v_mul_f32_e32 v75, v75, v81
	v_add_f32_e32 v78, 1.0, v78
	v_rcp_f32_e32 v78, v78
	s_nop 0
	v_mul_f32_e32 v75, v78, v75
	v_cndmask_b32_e32 v75, v78, v75, vcc
	v_mul_f32_e32 v78, 0xbfb8aa3b, v68
	v_exp_f32_e32 v78, v78
	v_mul_f32_e32 v68, v68, v82
	v_add_f32_e32 v78, 1.0, v78
	v_rcp_f32_e32 v78, v78
	s_nop 0
	v_mul_f32_e32 v68, v78, v68
	v_cndmask_b32_e32 v78, v78, v68, vcc
	v_mul_f32_e32 v68, 0xbfb8aa3b, v69
	v_exp_f32_e32 v68, v68
	v_mul_f32_e32 v69, v69, v83
	v_add_f32_e32 v68, 1.0, v68
	v_rcp_f32_e32 v68, v68
	s_nop 0
	v_mul_f32_e32 v69, v68, v69
	v_cndmask_b32_e32 v79, v68, v69, vcc
	v_mul_f32_e32 v68, 0xbfb8aa3b, v70
	v_exp_f32_e32 v68, v68
	v_mul_f32_e32 v69, v70, v84
	v_cvt_pk_bf16_f32 v70, v78, v79
	v_add_f32_e32 v68, 1.0, v68
	v_rcp_f32_e32 v68, v68
	s_nop 0
	v_mul_f32_e32 v69, v68, v69
	v_cndmask_b32_e32 v80, v68, v69, vcc
	v_mul_f32_e32 v68, 0xbfb8aa3b, v71
	v_exp_f32_e32 v68, v68
	v_mul_f32_e32 v69, v71, v85
	v_add_f32_e32 v68, 1.0, v68
	v_rcp_f32_e32 v68, v68
	s_nop 0
	v_mul_f32_e32 v69, v68, v69
	v_cndmask_b32_e32 v71, v68, v69, vcc
	v_cvt_pk_bf16_f32 v68, v72, v73
	v_cvt_pk_bf16_f32 v69, v74, v75
	v_cvt_pk_bf16_f32 v71, v80, v71
	global_store_dwordx4 v[76:77], v[68:71], off offset:256
	v_lshl_add_u64 v[102:103], v[188:189], 0, s[10:11]
	s_nop 0
	v_lshl_add_u64 v[68:69], s[52:53], 0, v[102:103]
	v_lshl_add_u64 v[68:69], v[68:69], 0, s[96:97]
	s_mov_b64 s[6:7], 0x48000
	v_lshl_add_u64 v[68:69], v[68:69], 0, v[2:3]
	v_lshl_add_u64 v[100:101], v[188:189], 0, s[6:7]
	s_cbranch_vccz .Lgates_skipld_3
	v_mov_b32_e32 v104, v216
	v_mov_b32_e32 v105, v217
	v_mov_b32_e32 v106, v218
	v_mov_b32_e32 v107, v219
	v_mov_b32_e32 v92, v224
	v_mov_b32_e32 v93, v225
	v_mov_b32_e32 v94, v226
	v_mov_b32_e32 v95, v227
.Lgates_skipld_3:
	v_lshl_add_u64 v[68:69], s[52:53], 0, v[100:101]
	v_lshl_add_u64 v[68:69], v[68:69], 0, s[96:97]
	s_mov_b64 s[6:7], 0x50000
	v_lshl_add_u64 v[68:69], v[68:69], 0, v[2:3]
	v_lshl_add_u64 v[98:99], v[188:189], 0, s[6:7]
	s_cbranch_vccz .Lgates_skipld_4
	v_mov_b32_e32 v88, v228
	v_mov_b32_e32 v89, v229
	v_mov_b32_e32 v90, v230
	v_mov_b32_e32 v91, v231
	v_mov_b32_e32 v84, v232
	v_mov_b32_e32 v85, v233
	v_mov_b32_e32 v86, v234
	v_mov_b32_e32 v87, v235
.Lgates_skipld_4:
	v_lshl_add_u64 v[68:69], s[52:53], 0, v[98:99]
	v_lshl_add_u64 v[68:69], v[68:69], 0, s[96:97]
	s_mov_b64 s[6:7], 0x58000
	v_lshl_add_u64 v[68:69], v[68:69], 0, v[2:3]
	v_lshl_add_u64 v[96:97], v[188:189], 0, s[6:7]
	s_cbranch_vccz .Lgates_skipld_5
	v_mov_b32_e32 v80, v236
	v_mov_b32_e32 v81, v237
	v_mov_b32_e32 v82, v238
	v_mov_b32_e32 v83, v239
	global_load_dwordx4 v[76:79], v[68:69], off offset:256
